# Swiglu fast-path (ACT) stores write-through sc1 instead of plain; on top of v28
# speedup vs baseline: 1.0028x; 1.0009x over previous
; __device__ __forceinline__ u32x4 pack8(const f32x4 a, const f32x4 b) { u32x4 w; w.x = cvt_pk_bf16(a[0], a[1]); w.y = cvt_pk_bf16(a[2], a[3]); w.z = cvt_pk_bf16(b[0], b[1]); w.w = cvt_pk_bf16(b[2], b[3]); return w; }
;     __device__ __forceinline__ void operator()(const f32x4 (&acc)[2][2][4][2], const Unit& u, int wr, int wc, int fr, int fq) const {
;     ...
;                 const int row = row0 + ai * 128 + m * 16; const float rs = (u.pm == pm0) ? RS[row & 255] : row_rstd(ss, row), rsl = -LOG2E_ * rs, rs2 = rs * rs;
;                 f32x4 t[2], q[2], e[2];
; #pragma unroll
;                 for (int n = 0; n < 2; ++n) { t[n] = acc[ai][0][m][n] * rsl; q[n] = acc[ai][0][m][n] * acc[ai][1][m][n]; }
; #pragma unroll
;                 for (int n = 0; n < 2; ++n)
; #pragma unroll
;                     for (int j = 0; j < 4; ++j) e[n][j] = __builtin_amdgcn_exp2f(t[n][j]);
; #pragma unroll
;                 for (int n = 0; n < 2; ++n) { e[n] = e[n] + 1.0f; q[n] = q[n] * rs2; }
; #pragma unroll
;                 for (int n = 0; n < 2; ++n)
; #pragma unroll
;                     for (int j = 0; j < 4; ++j) e[n][j] = __builtin_amdgcn_rcpf(e[n][j]);
;                 __builtin_nontemporal_store(pack8(q[0] * e[0], q[1] * e[1]), (u32x4*)(O + (size_t)row * DFF + col0));
.LBB0_228:
	s_cmp_lg_u32 s20, s29
	s_cbranch_scc1 .Lsw_slow
	v_lshl_add_u32 v146, s20, 8, v148
	v_lshl_or_b32 v147, s4, 7, v151
	v_mul_u32_u24_e32 v146, 0x1600, v146
	v_lshl_add_u32 v146, v147, 1, v146
	s_waitcnt lgkmcnt(7)
	v_mul_f32_e32 v140, 0xbfb8aa3b, v224
	v_mul_f32_e32 v138, v224, v224
	v_pk_mul_f32 v[154:155], v[126:127], v[140:141] op_sel_hi:[1,0]
	v_pk_mul_f32 v[156:157], v[128:129], v[140:141] op_sel_hi:[1,0]
	v_pk_mul_f32 v[158:159], v[122:123], v[140:141] op_sel_hi:[1,0]
	v_pk_mul_f32 v[160:161], v[124:125], v[140:141] op_sel_hi:[1,0]
	v_exp_f32_e32 v154, v154
	v_exp_f32_e32 v155, v155
	v_exp_f32_e32 v156, v156
	v_exp_f32_e32 v157, v157
	v_exp_f32_e32 v158, v158
	v_exp_f32_e32 v159, v159
	v_exp_f32_e32 v160, v160
	v_exp_f32_e32 v161, v161
	v_pk_mul_f32 v[118:119], v[126:127], v[118:119]
	v_pk_mul_f32 v[120:121], v[128:129], v[120:121]
	v_pk_mul_f32 v[114:115], v[122:123], v[114:115]
	v_pk_mul_f32 v[116:117], v[124:125], v[116:117]
	v_pk_add_f32 v[154:155], v[154:155], 1.0 op_sel_hi:[1,0]
	v_pk_add_f32 v[156:157], v[156:157], 1.0 op_sel_hi:[1,0]
	v_pk_add_f32 v[158:159], v[158:159], 1.0 op_sel_hi:[1,0]
	v_pk_add_f32 v[160:161], v[160:161], 1.0 op_sel_hi:[1,0]
	v_pk_mul_f32 v[118:119], v[118:119], v[138:139] op_sel_hi:[1,0]
	v_pk_mul_f32 v[120:121], v[120:121], v[138:139] op_sel_hi:[1,0]
	v_pk_mul_f32 v[114:115], v[114:115], v[138:139] op_sel_hi:[1,0]
	v_pk_mul_f32 v[116:117], v[116:117], v[138:139] op_sel_hi:[1,0]
	v_rcp_f32_e32 v154, v154
	v_rcp_f32_e32 v155, v155
	v_rcp_f32_e32 v156, v156
	v_rcp_f32_e32 v157, v157
	v_rcp_f32_e32 v158, v158
	v_rcp_f32_e32 v159, v159
	v_rcp_f32_e32 v160, v160
	v_rcp_f32_e32 v161, v161
	v_pk_mul_f32 v[118:119], v[118:119], v[154:155]
	v_pk_mul_f32 v[120:121], v[120:121], v[156:157]
	v_pk_mul_f32 v[114:115], v[114:115], v[158:159]
	v_pk_mul_f32 v[116:117], v[116:117], v[160:161]
	v_cvt_pk_bf16_f32 v126, v118, v119
	v_cvt_pk_bf16_f32 v127, v120, v121
	v_cvt_pk_bf16_f32 v128, v114, v115
	v_cvt_pk_bf16_f32 v129, v116, v117
	global_store_dwordx4 v146, v[126:129], s[36:37] sc1
	s_waitcnt lgkmcnt(6)
	v_mul_f32_e32 v140, 0xbfb8aa3b, v225
	v_mul_f32_e32 v138, v225, v225
	v_add_u32_e32 v147, 0x16000, v146
	v_pk_mul_f32 v[154:155], v[110:111], v[140:141] op_sel_hi:[1,0]
	v_pk_mul_f32 v[156:157], v[112:113], v[140:141] op_sel_hi:[1,0]
	v_pk_mul_f32 v[158:159], v[106:107], v[140:141] op_sel_hi:[1,0]
	v_pk_mul_f32 v[160:161], v[108:109], v[140:141] op_sel_hi:[1,0]
	v_exp_f32_e32 v154, v154
	v_exp_f32_e32 v155, v155
	v_exp_f32_e32 v156, v156
	v_exp_f32_e32 v157, v157
	v_exp_f32_e32 v158, v158
	v_exp_f32_e32 v159, v159
	v_exp_f32_e32 v160, v160
	v_exp_f32_e32 v161, v161
	v_pk_mul_f32 v[102:103], v[110:111], v[102:103]
	v_pk_mul_f32 v[104:105], v[112:113], v[104:105]
	v_pk_mul_f32 v[98:99], v[106:107], v[98:99]
	v_pk_mul_f32 v[100:101], v[108:109], v[100:101]
	v_pk_add_f32 v[154:155], v[154:155], 1.0 op_sel_hi:[1,0]
	v_pk_add_f32 v[156:157], v[156:157], 1.0 op_sel_hi:[1,0]
	v_pk_add_f32 v[158:159], v[158:159], 1.0 op_sel_hi:[1,0]
	v_pk_add_f32 v[160:161], v[160:161], 1.0 op_sel_hi:[1,0]
	v_pk_mul_f32 v[102:103], v[102:103], v[138:139] op_sel_hi:[1,0]
	v_pk_mul_f32 v[104:105], v[104:105], v[138:139] op_sel_hi:[1,0]
	v_pk_mul_f32 v[98:99], v[98:99], v[138:139] op_sel_hi:[1,0]
	v_pk_mul_f32 v[100:101], v[100:101], v[138:139] op_sel_hi:[1,0]
	v_rcp_f32_e32 v154, v154
	v_rcp_f32_e32 v155, v155
	v_rcp_f32_e32 v156, v156
	v_rcp_f32_e32 v157, v157
	v_rcp_f32_e32 v158, v158
	v_rcp_f32_e32 v159, v159
	v_rcp_f32_e32 v160, v160
	v_rcp_f32_e32 v161, v161
	v_pk_mul_f32 v[102:103], v[102:103], v[154:155]
	v_pk_mul_f32 v[104:105], v[104:105], v[156:157]
	v_pk_mul_f32 v[98:99], v[98:99], v[158:159]
	v_pk_mul_f32 v[100:101], v[100:101], v[160:161]
	v_cvt_pk_bf16_f32 v110, v102, v103
	v_cvt_pk_bf16_f32 v111, v104, v105
	v_cvt_pk_bf16_f32 v112, v98, v99
	v_cvt_pk_bf16_f32 v113, v100, v101
	global_store_dwordx4 v147, v[110:113], s[36:37] sc1
	s_waitcnt lgkmcnt(5)
	v_mul_f32_e32 v140, 0xbfb8aa3b, v226
	v_mul_f32_e32 v138, v226, v226
	v_add_u32_e32 v147, 0x2c000, v146
	v_pk_mul_f32 v[154:155], v[94:95], v[140:141] op_sel_hi:[1,0]
	v_pk_mul_f32 v[156:157], v[96:97], v[140:141] op_sel_hi:[1,0]
	v_pk_mul_f32 v[158:159], v[90:91], v[140:141] op_sel_hi:[1,0]
	v_pk_mul_f32 v[160:161], v[92:93], v[140:141] op_sel_hi:[1,0]
	v_exp_f32_e32 v154, v154
	v_exp_f32_e32 v155, v155
	v_exp_f32_e32 v156, v156
	v_exp_f32_e32 v157, v157
	v_exp_f32_e32 v158, v158
	v_exp_f32_e32 v159, v159
	v_exp_f32_e32 v160, v160
	v_exp_f32_e32 v161, v161
	v_pk_mul_f32 v[86:87], v[94:95], v[86:87]
	v_pk_mul_f32 v[88:89], v[96:97], v[88:89]
	v_pk_mul_f32 v[82:83], v[90:91], v[82:83]
	v_pk_mul_f32 v[84:85], v[92:93], v[84:85]
	v_pk_add_f32 v[154:155], v[154:155], 1.0 op_sel_hi:[1,0]
	v_pk_add_f32 v[156:157], v[156:157], 1.0 op_sel_hi:[1,0]
	v_pk_add_f32 v[158:159], v[158:159], 1.0 op_sel_hi:[1,0]
	v_pk_add_f32 v[160:161], v[160:161], 1.0 op_sel_hi:[1,0]
	v_pk_mul_f32 v[86:87], v[86:87], v[138:139] op_sel_hi:[1,0]
	v_pk_mul_f32 v[88:89], v[88:89], v[138:139] op_sel_hi:[1,0]
	v_pk_mul_f32 v[82:83], v[82:83], v[138:139] op_sel_hi:[1,0]
	v_pk_mul_f32 v[84:85], v[84:85], v[138:139] op_sel_hi:[1,0]
	v_rcp_f32_e32 v154, v154
	v_rcp_f32_e32 v155, v155
	v_rcp_f32_e32 v156, v156
	v_rcp_f32_e32 v157, v157
	v_rcp_f32_e32 v158, v158
	v_rcp_f32_e32 v159, v159
	v_rcp_f32_e32 v160, v160
	v_rcp_f32_e32 v161, v161
	v_pk_mul_f32 v[86:87], v[86:87], v[154:155]
	v_pk_mul_f32 v[88:89], v[88:89], v[156:157]
	v_pk_mul_f32 v[82:83], v[82:83], v[158:159]
	v_pk_mul_f32 v[84:85], v[84:85], v[160:161]
	v_cvt_pk_bf16_f32 v94, v86, v87
	v_cvt_pk_bf16_f32 v95, v88, v89
	v_cvt_pk_bf16_f32 v96, v82, v83
	v_cvt_pk_bf16_f32 v97, v84, v85
	global_store_dwordx4 v147, v[94:97], s[36:37] sc1
	s_waitcnt lgkmcnt(4)
; __device__ __forceinline__ u32x4 pack8(const f32x4 a, const f32x4 b) { u32x4 w; w.x = cvt_pk_bf16(a[0], a[1]); w.y = cvt_pk_bf16(a[2], a[3]); w.z = cvt_pk_bf16(b[0], b[1]); w.w = cvt_pk_bf16(b[2], b[3]); return w; }
;     __device__ __forceinline__ void operator()(const f32x4 (&acc)[2][2][4][2], const Unit& u, int wr, int wc, int fr, int fq) const {
;     ...
;                 const int row = row0 + ai * 128 + m * 16; const float rs = (u.pm == pm0) ? RS[row & 255] : row_rstd(ss, row), rsl = -LOG2E_ * rs, rs2 = rs * rs;
;                 f32x4 t[2], q[2], e[2];
; #pragma unroll
;                 for (int n = 0; n < 2; ++n) { t[n] = acc[ai][0][m][n] * rsl; q[n] = acc[ai][0][m][n] * acc[ai][1][m][n]; }
; #pragma unroll
;                 for (int n = 0; n < 2; ++n)
; #pragma unroll
;                     for (int j = 0; j < 4; ++j) e[n][j] = __builtin_amdgcn_exp2f(t[n][j]);
; #pragma unroll
;                 for (int n = 0; n < 2; ++n) { e[n] = e[n] + 1.0f; q[n] = q[n] * rs2; }
; #pragma unroll
;                 for (int n = 0; n < 2; ++n)
; #pragma unroll
;                     for (int j = 0; j < 4; ++j) e[n][j] = __builtin_amdgcn_rcpf(e[n][j]);
;                 __builtin_nontemporal_store(pack8(q[0] * e[0], q[1] * e[1]), (u32x4*)(O + (size_t)row * DFF + col0));
	v_mul_f32_e32 v140, 0xbfb8aa3b, v227
	v_mul_f32_e32 v138, v227, v227
	v_add_u32_e32 v147, 0x42000, v146
	v_pk_mul_f32 v[154:155], v[78:79], v[140:141] op_sel_hi:[1,0]
	v_pk_mul_f32 v[156:157], v[80:81], v[140:141] op_sel_hi:[1,0]
	v_pk_mul_f32 v[158:159], v[74:75], v[140:141] op_sel_hi:[1,0]
	v_pk_mul_f32 v[160:161], v[76:77], v[140:141] op_sel_hi:[1,0]
	v_exp_f32_e32 v154, v154
	v_exp_f32_e32 v155, v155
	v_exp_f32_e32 v156, v156
	v_exp_f32_e32 v157, v157
	v_exp_f32_e32 v158, v158
	v_exp_f32_e32 v159, v159
	v_exp_f32_e32 v160, v160
	v_exp_f32_e32 v161, v161
	v_pk_mul_f32 v[70:71], v[78:79], v[70:71]
	v_pk_mul_f32 v[72:73], v[80:81], v[72:73]
	v_pk_mul_f32 v[66:67], v[74:75], v[66:67]
	v_pk_mul_f32 v[68:69], v[76:77], v[68:69]
	v_pk_add_f32 v[154:155], v[154:155], 1.0 op_sel_hi:[1,0]
	v_pk_add_f32 v[156:157], v[156:157], 1.0 op_sel_hi:[1,0]
	v_pk_add_f32 v[158:159], v[158:159], 1.0 op_sel_hi:[1,0]
	v_pk_add_f32 v[160:161], v[160:161], 1.0 op_sel_hi:[1,0]
	v_pk_mul_f32 v[70:71], v[70:71], v[138:139] op_sel_hi:[1,0]
	v_pk_mul_f32 v[72:73], v[72:73], v[138:139] op_sel_hi:[1,0]
	v_pk_mul_f32 v[66:67], v[66:67], v[138:139] op_sel_hi:[1,0]
	v_pk_mul_f32 v[68:69], v[68:69], v[138:139] op_sel_hi:[1,0]
	v_rcp_f32_e32 v154, v154
	v_rcp_f32_e32 v155, v155
	v_rcp_f32_e32 v156, v156
	v_rcp_f32_e32 v157, v157
	v_rcp_f32_e32 v158, v158
	v_rcp_f32_e32 v159, v159
	v_rcp_f32_e32 v160, v160
	v_rcp_f32_e32 v161, v161
	v_pk_mul_f32 v[70:71], v[70:71], v[154:155]
	v_pk_mul_f32 v[72:73], v[72:73], v[156:157]
	v_pk_mul_f32 v[66:67], v[66:67], v[158:159]
	v_pk_mul_f32 v[68:69], v[68:69], v[160:161]
	v_cvt_pk_bf16_f32 v78, v70, v71
	v_cvt_pk_bf16_f32 v79, v72, v73
	v_cvt_pk_bf16_f32 v80, v66, v67
	v_cvt_pk_bf16_f32 v81, v68, v69
	global_store_dwordx4 v147, v[78:81], s[36:37] sc1
	s_waitcnt lgkmcnt(3)
	v_mul_f32_e32 v140, 0xbfb8aa3b, v228
	v_mul_f32_e32 v138, v228, v228
	v_add_u32_e32 v147, 0xb0000, v146
	v_pk_mul_f32 v[154:155], v[62:63], v[140:141] op_sel_hi:[1,0]
	v_pk_mul_f32 v[156:157], v[64:65], v[140:141] op_sel_hi:[1,0]
	v_pk_mul_f32 v[158:159], v[58:59], v[140:141] op_sel_hi:[1,0]
	v_pk_mul_f32 v[160:161], v[60:61], v[140:141] op_sel_hi:[1,0]
	v_exp_f32_e32 v154, v154
	v_exp_f32_e32 v155, v155
	v_exp_f32_e32 v156, v156
	v_exp_f32_e32 v157, v157
	v_exp_f32_e32 v158, v158
	v_exp_f32_e32 v159, v159
	v_exp_f32_e32 v160, v160
	v_exp_f32_e32 v161, v161
	v_pk_mul_f32 v[54:55], v[62:63], v[54:55]
	v_pk_mul_f32 v[56:57], v[64:65], v[56:57]
	v_pk_mul_f32 v[50:51], v[58:59], v[50:51]
	v_pk_mul_f32 v[52:53], v[60:61], v[52:53]
	v_pk_add_f32 v[154:155], v[154:155], 1.0 op_sel_hi:[1,0]
	v_pk_add_f32 v[156:157], v[156:157], 1.0 op_sel_hi:[1,0]
	v_pk_add_f32 v[158:159], v[158:159], 1.0 op_sel_hi:[1,0]
	v_pk_add_f32 v[160:161], v[160:161], 1.0 op_sel_hi:[1,0]
	v_pk_mul_f32 v[54:55], v[54:55], v[138:139] op_sel_hi:[1,0]
	v_pk_mul_f32 v[56:57], v[56:57], v[138:139] op_sel_hi:[1,0]
	v_pk_mul_f32 v[50:51], v[50:51], v[138:139] op_sel_hi:[1,0]
	v_pk_mul_f32 v[52:53], v[52:53], v[138:139] op_sel_hi:[1,0]
	v_rcp_f32_e32 v154, v154
	v_rcp_f32_e32 v155, v155
	v_rcp_f32_e32 v156, v156
	v_rcp_f32_e32 v157, v157
	v_rcp_f32_e32 v158, v158
	v_rcp_f32_e32 v159, v159
	v_rcp_f32_e32 v160, v160
	v_rcp_f32_e32 v161, v161
	v_pk_mul_f32 v[54:55], v[54:55], v[154:155]
	v_pk_mul_f32 v[56:57], v[56:57], v[156:157]
	v_pk_mul_f32 v[50:51], v[50:51], v[158:159]
	v_pk_mul_f32 v[52:53], v[52:53], v[160:161]
	v_cvt_pk_bf16_f32 v62, v54, v55
	v_cvt_pk_bf16_f32 v63, v56, v57
	v_cvt_pk_bf16_f32 v64, v50, v51
	v_cvt_pk_bf16_f32 v65, v52, v53
	global_store_dwordx4 v147, v[62:65], s[36:37] sc1
	s_waitcnt lgkmcnt(2)
	v_mul_f32_e32 v140, 0xbfb8aa3b, v229
	v_mul_f32_e32 v138, v229, v229
	v_add_u32_e32 v147, 0xc6000, v146
	v_pk_mul_f32 v[154:155], v[46:47], v[140:141] op_sel_hi:[1,0]
	v_pk_mul_f32 v[156:157], v[48:49], v[140:141] op_sel_hi:[1,0]
	v_pk_mul_f32 v[158:159], v[42:43], v[140:141] op_sel_hi:[1,0]
	v_pk_mul_f32 v[160:161], v[44:45], v[140:141] op_sel_hi:[1,0]
	v_exp_f32_e32 v154, v154
	v_exp_f32_e32 v155, v155
	v_exp_f32_e32 v156, v156
	v_exp_f32_e32 v157, v157
	v_exp_f32_e32 v158, v158
	v_exp_f32_e32 v159, v159
	v_exp_f32_e32 v160, v160
	v_exp_f32_e32 v161, v161
	v_pk_mul_f32 v[38:39], v[46:47], v[38:39]
	v_pk_mul_f32 v[40:41], v[48:49], v[40:41]
	v_pk_mul_f32 v[34:35], v[42:43], v[34:35]
	v_pk_mul_f32 v[36:37], v[44:45], v[36:37]
	v_pk_add_f32 v[154:155], v[154:155], 1.0 op_sel_hi:[1,0]
	v_pk_add_f32 v[156:157], v[156:157], 1.0 op_sel_hi:[1,0]
	v_pk_add_f32 v[158:159], v[158:159], 1.0 op_sel_hi:[1,0]
	v_pk_add_f32 v[160:161], v[160:161], 1.0 op_sel_hi:[1,0]
	v_pk_mul_f32 v[38:39], v[38:39], v[138:139] op_sel_hi:[1,0]
	v_pk_mul_f32 v[40:41], v[40:41], v[138:139] op_sel_hi:[1,0]
	v_pk_mul_f32 v[34:35], v[34:35], v[138:139] op_sel_hi:[1,0]
	v_pk_mul_f32 v[36:37], v[36:37], v[138:139] op_sel_hi:[1,0]
	v_rcp_f32_e32 v154, v154
	v_rcp_f32_e32 v155, v155
	v_rcp_f32_e32 v156, v156
	v_rcp_f32_e32 v157, v157
	v_rcp_f32_e32 v158, v158
	v_rcp_f32_e32 v159, v159
	v_rcp_f32_e32 v160, v160
	v_rcp_f32_e32 v161, v161
	v_pk_mul_f32 v[38:39], v[38:39], v[154:155]
	v_pk_mul_f32 v[40:41], v[40:41], v[156:157]
	v_pk_mul_f32 v[34:35], v[34:35], v[158:159]
	v_pk_mul_f32 v[36:37], v[36:37], v[160:161]
	v_cvt_pk_bf16_f32 v46, v38, v39
	v_cvt_pk_bf16_f32 v47, v40, v41
	v_cvt_pk_bf16_f32 v48, v34, v35
	v_cvt_pk_bf16_f32 v49, v36, v37
	global_store_dwordx4 v147, v[46:49], s[36:37] sc1
	s_waitcnt lgkmcnt(1)
; __device__ __forceinline__ u32x4 pack8(const f32x4 a, const f32x4 b) { u32x4 w; w.x = cvt_pk_bf16(a[0], a[1]); w.y = cvt_pk_bf16(a[2], a[3]); w.z = cvt_pk_bf16(b[0], b[1]); w.w = cvt_pk_bf16(b[2], b[3]); return w; }
;     __device__ __forceinline__ void operator()(const f32x4 (&acc)[2][2][4][2], const Unit& u, int wr, int wc, int fr, int fq) const {
;     ...
;                 const int row = row0 + ai * 128 + m * 16; const float rs = (u.pm == pm0) ? RS[row & 255] : row_rstd(ss, row), rsl = -LOG2E_ * rs, rs2 = rs * rs;
;                 f32x4 t[2], q[2], e[2];
; #pragma unroll
;                 for (int n = 0; n < 2; ++n) { t[n] = acc[ai][0][m][n] * rsl; q[n] = acc[ai][0][m][n] * acc[ai][1][m][n]; }
; #pragma unroll
;                 for (int n = 0; n < 2; ++n)
; #pragma unroll
;                     for (int j = 0; j < 4; ++j) e[n][j] = __builtin_amdgcn_exp2f(t[n][j]);
; #pragma unroll
;                 for (int n = 0; n < 2; ++n) { e[n] = e[n] + 1.0f; q[n] = q[n] * rs2; }
; #pragma unroll
;                 for (int n = 0; n < 2; ++n)
; #pragma unroll
;                     for (int j = 0; j < 4; ++j) e[n][j] = __builtin_amdgcn_rcpf(e[n][j]);
;                 __builtin_nontemporal_store(pack8(q[0] * e[0], q[1] * e[1]), (u32x4*)(O + (size_t)row * DFF + col0));
	v_mul_f32_e32 v140, 0xbfb8aa3b, v230
	v_mul_f32_e32 v138, v230, v230
	v_add_u32_e32 v147, 0xdc000, v146
	v_pk_mul_f32 v[154:155], v[30:31], v[140:141] op_sel_hi:[1,0]
	v_pk_mul_f32 v[156:157], v[32:33], v[140:141] op_sel_hi:[1,0]
	v_pk_mul_f32 v[158:159], v[26:27], v[140:141] op_sel_hi:[1,0]
	v_pk_mul_f32 v[160:161], v[28:29], v[140:141] op_sel_hi:[1,0]
	v_exp_f32_e32 v154, v154
	v_exp_f32_e32 v155, v155
	v_exp_f32_e32 v156, v156
	v_exp_f32_e32 v157, v157
	v_exp_f32_e32 v158, v158
	v_exp_f32_e32 v159, v159
	v_exp_f32_e32 v160, v160
	v_exp_f32_e32 v161, v161
	v_pk_mul_f32 v[22:23], v[30:31], v[22:23]
	v_pk_mul_f32 v[24:25], v[32:33], v[24:25]
	v_pk_mul_f32 v[18:19], v[26:27], v[18:19]
	v_pk_mul_f32 v[20:21], v[28:29], v[20:21]
	v_pk_add_f32 v[154:155], v[154:155], 1.0 op_sel_hi:[1,0]
	v_pk_add_f32 v[156:157], v[156:157], 1.0 op_sel_hi:[1,0]
	v_pk_add_f32 v[158:159], v[158:159], 1.0 op_sel_hi:[1,0]
	v_pk_add_f32 v[160:161], v[160:161], 1.0 op_sel_hi:[1,0]
	v_pk_mul_f32 v[22:23], v[22:23], v[138:139] op_sel_hi:[1,0]
	v_pk_mul_f32 v[24:25], v[24:25], v[138:139] op_sel_hi:[1,0]
	v_pk_mul_f32 v[18:19], v[18:19], v[138:139] op_sel_hi:[1,0]
	v_pk_mul_f32 v[20:21], v[20:21], v[138:139] op_sel_hi:[1,0]
	v_rcp_f32_e32 v154, v154
	v_rcp_f32_e32 v155, v155
	v_rcp_f32_e32 v156, v156
	v_rcp_f32_e32 v157, v157
	v_rcp_f32_e32 v158, v158
	v_rcp_f32_e32 v159, v159
	v_rcp_f32_e32 v160, v160
	v_rcp_f32_e32 v161, v161
	v_pk_mul_f32 v[22:23], v[22:23], v[154:155]
	v_pk_mul_f32 v[24:25], v[24:25], v[156:157]
	v_pk_mul_f32 v[18:19], v[18:19], v[158:159]
	v_pk_mul_f32 v[20:21], v[20:21], v[160:161]
	v_cvt_pk_bf16_f32 v30, v22, v23
	v_cvt_pk_bf16_f32 v31, v24, v25
	v_cvt_pk_bf16_f32 v32, v18, v19
	v_cvt_pk_bf16_f32 v33, v20, v21
	global_store_dwordx4 v147, v[30:33], s[36:37] sc1
	s_waitcnt lgkmcnt(0)
	v_mul_f32_e32 v140, 0xbfb8aa3b, v231
	v_mul_f32_e32 v138, v231, v231
	v_add_u32_e32 v147, 0xf2000, v146
	v_pk_mul_f32 v[154:155], v[14:15], v[140:141] op_sel_hi:[1,0]
	v_pk_mul_f32 v[156:157], v[16:17], v[140:141] op_sel_hi:[1,0]
	v_pk_mul_f32 v[158:159], v[10:11], v[140:141] op_sel_hi:[1,0]
	v_pk_mul_f32 v[160:161], v[12:13], v[140:141] op_sel_hi:[1,0]
	v_exp_f32_e32 v154, v154
	v_exp_f32_e32 v155, v155
	v_exp_f32_e32 v156, v156
	v_exp_f32_e32 v157, v157
	v_exp_f32_e32 v158, v158
	v_exp_f32_e32 v159, v159
	v_exp_f32_e32 v160, v160
	v_exp_f32_e32 v161, v161
	v_pk_mul_f32 v[6:7], v[14:15], v[6:7]
	v_pk_mul_f32 v[8:9], v[16:17], v[8:9]
	v_pk_mul_f32 v[2:3], v[10:11], v[2:3]
	v_pk_mul_f32 v[4:5], v[12:13], v[4:5]
	v_pk_add_f32 v[154:155], v[154:155], 1.0 op_sel_hi:[1,0]
	v_pk_add_f32 v[156:157], v[156:157], 1.0 op_sel_hi:[1,0]
	v_pk_add_f32 v[158:159], v[158:159], 1.0 op_sel_hi:[1,0]
	v_pk_add_f32 v[160:161], v[160:161], 1.0 op_sel_hi:[1,0]
	v_pk_mul_f32 v[6:7], v[6:7], v[138:139] op_sel_hi:[1,0]
	v_pk_mul_f32 v[8:9], v[8:9], v[138:139] op_sel_hi:[1,0]
	v_pk_mul_f32 v[2:3], v[2:3], v[138:139] op_sel_hi:[1,0]
	v_pk_mul_f32 v[4:5], v[4:5], v[138:139] op_sel_hi:[1,0]
	v_rcp_f32_e32 v154, v154
	v_rcp_f32_e32 v155, v155
	v_rcp_f32_e32 v156, v156
	v_rcp_f32_e32 v157, v157
	v_rcp_f32_e32 v158, v158
	v_rcp_f32_e32 v159, v159
	v_rcp_f32_e32 v160, v160
	v_rcp_f32_e32 v161, v161
	v_pk_mul_f32 v[6:7], v[6:7], v[154:155]
	v_pk_mul_f32 v[8:9], v[8:9], v[156:157]
	v_pk_mul_f32 v[2:3], v[2:3], v[158:159]
	v_pk_mul_f32 v[4:5], v[4:5], v[160:161]
	v_cvt_pk_bf16_f32 v14, v6, v7
	v_cvt_pk_bf16_f32 v15, v8, v9
	v_cvt_pk_bf16_f32 v16, v2, v3
	v_cvt_pk_bf16_f32 v17, v4, v5
	global_store_dwordx4 v147, v[14:17], s[36:37] sc1
	s_andn2_b64 vcc, exec, s[2:3]
	s_mov_b64 s[2:3], -1
	s_cbranch_vccnz .LBB0_221
	s_branch .Lsw_join
